# P3 RWKV loader waves (the slowest role): loader roles dispatched first, one range test in the common path, transposed k/nb LDS writes issued before the remaining exponentials
# speedup vs baseline: 1.0063x; 1.0025x over previous
; template <bool RWKV> __device__ __forceinline__ void scan_item(LAS unsigned char* lds, const ScanSrc& S, int wid, int lane) {
;     ...
;     for (int c = 0; c < NCH; ++c) {
;         const int i1 = i0 == 2 ? 0 : i0 + 1, i2 = i1 == 2 ? 0 : i1 + 1;
;         if (is_ld) {
;             if (c + 3 < NCH) scan_load_finish<RWKV>(lds + ((b0 + 3) & 3) * SC_BUF, L, lt);
;             if (c + 4 < NCH) scan_load_issue<RWKV>(L, S, c + 4, lt); }
;         else if (is_prep) { if (c + 2 < NCH) scan_prep_m1<RWKV>(lds + ((b0 + 2) & 3) * SC_BUF, lds + SC_IMG + i2 * SW_SIZE, lane); }
;         else if (is_inv) { if (c + 1 < NCH) scan_prep_inv<RWKV>(lds + SC_IMG + i1 * SW_SIZE, lane); }
;         else if (wid < 2) scan_chunk<RWKV>(lds + b0 * SC_BUF, lds + SC_IMG + i0 * SW_SIZE, T, S, c, wid, lane);
.LBB0_614:
	s_bitcmp1_b32 0xb8, s3
	s_cbranch_scc1 .LBB0_640
	s_add_i32 s0, s72, 1
	s_cmp_lg_u32 s72, 2
	s_cselect_b32 s71, s0, 0
	s_cmp_lt_i32 s3, 2
	s_cbranch_scc1 .Lrw_compute
	s_cmp_eq_u32 s3, 2
	s_cbranch_scc1 .Lrw_prep
	s_branch .Lrw_inv

; __device__ __forceinline__ void unpack4(const u32x2 w, float (&f)[4]) { f[0] = bflo(w.x); f[1] = bfhi(w.x); f[2] = bflo(w.y); f[3] = bfhi(w.y); }
; template <bool RWKV> __device__ __forceinline__ void scan_load_finish(LAS unsigned char* buf, const ScanLd& L, int lt) {
;     const int lw = lt >> 6, lane = lt & 63, sl = lane >> 2, col = 16 * lw + 4 * (lane & 3);
;     float d[4], c[4], k[4], r[4], v[4], kk[4], nb[4];
;     unpack4(L.rd, d); unpack4(L.rk, k); unpack4(L.rr, r); unpack4(L.rv, v); unpack4(L.rkk, kk); unpack4(L.rnb, nb);
; #pragma unroll
;     for (int i = 0; i < 4; ++i) c[i] = d[i];
; #pragma unroll
;     for (int dl = 4; dl < 64; dl <<= 1)
; #pragma unroll
;         for (int i = 0; i < 4; ++i) { const float t = __shfl_up(c[i], dl); c[i] += (lane >= dl) ? t : 0.f; }
;     float o1[4], o2[4], o3[4], o4[4]; f32x4 we;
; #pragma unroll
;     for (int i = 0; i < 4; ++i) { const float W = __expf(-c[i]), iW = __expf(c[i]), Wp = __expf(d[i] - c[i]); o1[i] = RWKV ? kk[i] * Wp : 0.f; o2[i] = RWKV ? nb[i] * iW : 0.f; o3[i] = k[i] * iW; o4[i] = r[i] * W; we[i] = W; }
;     u32x2 w;
;     w.x = cvt2(o1[0], o1[1]); w.y = cvt2(o1[2], o1[3]); *(LAS u32x2*)(buf + SB_XA + sl * 144 + col * 2) = w;
;     w.x = cvt2(o4[0], o4[1]); w.y = cvt2(o4[2], o4[3]); *(LAS u32x2*)(buf + SB_XA + (16 + sl) * 144 + col * 2) = w;
;     w.x = cvt2(o2[0], o2[1]); w.y = cvt2(o2[2], o2[3]); *(LAS u32x2*)(buf + SB_XB + sl * 144 + col * 2) = w;
;     w.x = cvt2(o3[0], o3[1]); w.y = cvt2(o3[2], o3[3]); *(LAS u32x2*)(buf + SB_XB + (16 + sl) * 144 + col * 2) = w;
; #pragma unroll
;     for (int i = 0; i < 4; ++i) {
;         *(LAS unsigned short*)(buf + SB_XBT + (col + i) * 80 + sl * 2) = (unsigned short)(cvt2(o2[i], 0.f) & 0xffffu);
;         *(LAS unsigned short*)(buf + SB_XBT + (col + i) * 80 + (16 + sl) * 2) = (unsigned short)(cvt2(o3[i], 0.f) & 0xffffu);
;         *(LAS unsigned short*)(buf + SB_VT + (col + i) * 48 + sl * 2) = (unsigned short)(cvt2(v[i], 0.f) & 0xffffu); }
; template <bool RWKV> __device__ __forceinline__ void scan_item(LAS unsigned char* lds, const ScanSrc& S, int wid, int lane) {
;     ...
;         if (is_ld) {
;             if (c + 3 < NCH) scan_load_finish<RWKV>(lds + ((b0 + 3) & 3) * SC_BUF, L, lt);
;             if (c + 4 < NCH) scan_load_issue<RWKV>(L, S, c + 4, lt); }
.LBB0_640:
	s_cmpk_gt_u32 s69, 0xfa
	s_cbranch_scc1 .Lrw_ld_rare
	s_add_i32 s0, s70, -1
	s_and_b32 s0, s0, 3
	s_mulk_i32 s0, 0x4500
	v_add_u32_e32 v190, s0, v250
	s_bitcmp1_b32 s69, 0
	s_cbranch_scc1 .Lrw_ld_odd
	s_waitcnt vmcnt(6)
	v_lshlrev_b32_e32 v32, 16, v76
	v_and_b32_e32 v33, 0xffff0000, v76
	v_lshlrev_b32_e32 v34, 16, v77
	v_and_b32_e32 v35, 0xffff0000, v77
	v_mul_f32_e32 v52, 0x3fb8aa3b, v32
	v_mul_f32_e32 v53, 0x3fb8aa3b, v33
	v_mul_f32_e32 v54, 0x3fb8aa3b, v34
	v_mul_f32_e32 v55, 0x3fb8aa3b, v35
	v_add_f32_dpp v52, v52, v52 row_shr:4 row_mask:0xf bank_mask:0xf
	v_add_f32_dpp v53, v53, v53 row_shr:4 row_mask:0xf bank_mask:0xf
	v_add_f32_dpp v54, v54, v54 row_shr:4 row_mask:0xf bank_mask:0xf
	v_add_f32_dpp v55, v55, v55 row_shr:4 row_mask:0xf bank_mask:0xf
	v_add_f32_dpp v52, v52, v52 row_shr:8 row_mask:0xf bank_mask:0xf
	v_add_f32_dpp v53, v53, v53 row_shr:8 row_mask:0xf bank_mask:0xf
	v_add_f32_dpp v54, v54, v54 row_shr:8 row_mask:0xf bank_mask:0xf
	v_add_f32_dpp v55, v55, v55 row_shr:8 row_mask:0xf bank_mask:0xf
	ds_bpermute_b32 v60, v251, v52
	ds_bpermute_b32 v61, v251, v53
	ds_bpermute_b32 v62, v251, v54
	ds_bpermute_b32 v63, v251, v55
	ds_write_b16 v190, v82 offset:14336
	ds_write_b16_d16_hi v190, v82 offset:14384
	ds_write_b16 v190, v83 offset:14432
	ds_write_b16_d16_hi v190, v83 offset:14480
	v_lshlrev_b32_e32 v36, 16, v78
	v_and_b32_e32 v37, 0xffff0000, v78
	v_lshlrev_b32_e32 v38, 16, v79
	v_and_b32_e32 v39, 0xffff0000, v79
	v_lshlrev_b32_e32 v40, 16, v80
	v_and_b32_e32 v41, 0xffff0000, v80
	v_lshlrev_b32_e32 v42, 16, v81
	v_and_b32_e32 v43, 0xffff0000, v81
	v_lshlrev_b32_e32 v44, 16, v84
	v_and_b32_e32 v45, 0xffff0000, v84
	v_lshlrev_b32_e32 v46, 16, v85
	v_and_b32_e32 v47, 0xffff0000, v85
	v_lshlrev_b32_e32 v48, 16, v86
	v_and_b32_e32 v49, 0xffff0000, v86
	v_lshlrev_b32_e32 v50, 16, v87
	v_and_b32_e32 v51, 0xffff0000, v87
	s_waitcnt lgkmcnt(4)
	v_fmac_f32_e32 v52, v60, v253
	v_fmac_f32_e32 v53, v61, v253
	v_fmac_f32_e32 v54, v62, v253
	v_fmac_f32_e32 v55, v63, v253
	ds_bpermute_b32 v60, v252, v52
	ds_bpermute_b32 v61, v252, v53
	ds_bpermute_b32 v62, v252, v54
	ds_bpermute_b32 v63, v252, v55
	global_load_dwordx2 v[76:77], v[234:235], off
	global_load_dwordx2 v[78:79], v[236:237], off
	global_load_dwordx2 v[80:81], v[238:239], off
	global_load_dwordx2 v[82:83], v[240:241], off
	global_load_dwordx2 v[84:85], v[242:243], off
	global_load_dwordx2 v[86:87], v[246:247], off
	v_lshl_add_u64 v[234:235], v[234:235], 0, s[98:99]
	v_lshl_add_u64 v[236:237], v[236:237], 0, s[100:101]
	v_lshl_add_u64 v[238:239], v[238:239], 0, s[100:101]
	v_lshl_add_u64 v[240:241], v[240:241], 0, s[100:101]
	v_lshl_add_u64 v[242:243], v[242:243], 0, s[98:99]
	v_lshl_add_u64 v[246:247], v[246:247], 0, s[98:99]
	s_waitcnt lgkmcnt(0)
	v_fmac_f32_e32 v52, v60, v245
	v_fmac_f32_e32 v53, v61, v245
	v_fmac_f32_e32 v54, v62, v245
	v_fmac_f32_e32 v55, v63, v245
	s_branch .Lrw_ldfin
.Lrw_ld_odd:
	s_waitcnt vmcnt(6)
	v_lshlrev_b32_e32 v32, 16, v222
	v_and_b32_e32 v33, 0xffff0000, v222
	v_lshlrev_b32_e32 v34, 16, v223
	v_and_b32_e32 v35, 0xffff0000, v223
	v_mul_f32_e32 v52, 0x3fb8aa3b, v32
	v_mul_f32_e32 v53, 0x3fb8aa3b, v33
	v_mul_f32_e32 v54, 0x3fb8aa3b, v34
	v_mul_f32_e32 v55, 0x3fb8aa3b, v35
	v_add_f32_dpp v52, v52, v52 row_shr:4 row_mask:0xf bank_mask:0xf
	v_add_f32_dpp v53, v53, v53 row_shr:4 row_mask:0xf bank_mask:0xf
	v_add_f32_dpp v54, v54, v54 row_shr:4 row_mask:0xf bank_mask:0xf
	v_add_f32_dpp v55, v55, v55 row_shr:4 row_mask:0xf bank_mask:0xf
	v_add_f32_dpp v52, v52, v52 row_shr:8 row_mask:0xf bank_mask:0xf
	v_add_f32_dpp v53, v53, v53 row_shr:8 row_mask:0xf bank_mask:0xf
	v_add_f32_dpp v54, v54, v54 row_shr:8 row_mask:0xf bank_mask:0xf
	v_add_f32_dpp v55, v55, v55 row_shr:8 row_mask:0xf bank_mask:0xf
	ds_bpermute_b32 v60, v251, v52
	ds_bpermute_b32 v61, v251, v53
	ds_bpermute_b32 v62, v251, v54
	ds_bpermute_b32 v63, v251, v55
	ds_write_b16 v190, v228 offset:14336
	ds_write_b16_d16_hi v190, v228 offset:14384
	ds_write_b16 v190, v229 offset:14432
	ds_write_b16_d16_hi v190, v229 offset:14480
	v_lshlrev_b32_e32 v36, 16, v224
	v_and_b32_e32 v37, 0xffff0000, v224
	v_lshlrev_b32_e32 v38, 16, v225
	v_and_b32_e32 v39, 0xffff0000, v225
	v_lshlrev_b32_e32 v40, 16, v226
	v_and_b32_e32 v41, 0xffff0000, v226
	v_lshlrev_b32_e32 v42, 16, v227
	v_and_b32_e32 v43, 0xffff0000, v227
	v_lshlrev_b32_e32 v44, 16, v230
	v_and_b32_e32 v45, 0xffff0000, v230
	v_lshlrev_b32_e32 v46, 16, v231
	v_and_b32_e32 v47, 0xffff0000, v231
	v_lshlrev_b32_e32 v48, 16, v232
	v_and_b32_e32 v49, 0xffff0000, v232
	v_lshlrev_b32_e32 v50, 16, v233
	v_and_b32_e32 v51, 0xffff0000, v233
	s_waitcnt lgkmcnt(4)
	v_fmac_f32_e32 v52, v60, v253
	v_fmac_f32_e32 v53, v61, v253
	v_fmac_f32_e32 v54, v62, v253
	v_fmac_f32_e32 v55, v63, v253
	ds_bpermute_b32 v60, v252, v52
	ds_bpermute_b32 v61, v252, v53
	ds_bpermute_b32 v62, v252, v54
	ds_bpermute_b32 v63, v252, v55
	global_load_dwordx2 v[222:223], v[234:235], off
	global_load_dwordx2 v[224:225], v[236:237], off
	global_load_dwordx2 v[226:227], v[238:239], off
	global_load_dwordx2 v[228:229], v[240:241], off
	global_load_dwordx2 v[230:231], v[242:243], off
	global_load_dwordx2 v[232:233], v[246:247], off
	v_lshl_add_u64 v[234:235], v[234:235], 0, s[98:99]
	v_lshl_add_u64 v[236:237], v[236:237], 0, s[100:101]
	v_lshl_add_u64 v[238:239], v[238:239], 0, s[100:101]
	v_lshl_add_u64 v[240:241], v[240:241], 0, s[100:101]
	v_lshl_add_u64 v[242:243], v[242:243], 0, s[98:99]
	v_lshl_add_u64 v[246:247], v[246:247], 0, s[98:99]
	s_waitcnt lgkmcnt(0)
	v_fmac_f32_e32 v52, v60, v245
	v_fmac_f32_e32 v53, v61, v245
	v_fmac_f32_e32 v54, v62, v245
	v_fmac_f32_e32 v55, v63, v245
	s_branch .Lrw_ldfin
; __device__ __forceinline__ void unpack4(const u32x2 w, float (&f)[4]) { f[0] = bflo(w.x); f[1] = bfhi(w.x); f[2] = bflo(w.y); f[3] = bfhi(w.y); }
; __device__ __forceinline__ unsigned cvt2(float a, float b) { f32x2 v = {a, b}; bf16x2_t r = __builtin_convertvector(v, bf16x2_t); return __builtin_bit_cast(unsigned, r); }
; template <bool RWKV> __device__ __forceinline__ void scan_load_finish(LAS unsigned char* buf, const ScanLd& L, int lt) {
;     const int lw = lt >> 6, lane = lt & 63, sl = lane >> 2, col = 16 * lw + 4 * (lane & 3);
;     float d[4], c[4], k[4], r[4], v[4], kk[4], nb[4];
;     unpack4(L.rd, d); unpack4(L.rk, k); unpack4(L.rr, r); unpack4(L.rv, v); unpack4(L.rkk, kk); unpack4(L.rnb, nb);
; #pragma unroll
;     for (int i = 0; i < 4; ++i) c[i] = d[i];
; #pragma unroll
;     for (int dl = 4; dl < 64; dl <<= 1)
; #pragma unroll
;         for (int i = 0; i < 4; ++i) { const float t = __shfl_up(c[i], dl); c[i] += (lane >= dl) ? t : 0.f; }
;     float o1[4], o2[4], o3[4], o4[4]; f32x4 we;
; #pragma unroll
;     for (int i = 0; i < 4; ++i) { const float W = __expf(-c[i]), iW = __expf(c[i]), Wp = __expf(d[i] - c[i]); o1[i] = RWKV ? kk[i] * Wp : 0.f; o2[i] = RWKV ? nb[i] * iW : 0.f; o3[i] = k[i] * iW; o4[i] = r[i] * W; we[i] = W; }
;     u32x2 w;
;     w.x = cvt2(o1[0], o1[1]); w.y = cvt2(o1[2], o1[3]); *(LAS u32x2*)(buf + SB_XA + sl * 144 + col * 2) = w;
;     w.x = cvt2(o4[0], o4[1]); w.y = cvt2(o4[2], o4[3]); *(LAS u32x2*)(buf + SB_XA + (16 + sl) * 144 + col * 2) = w;
;     w.x = cvt2(o2[0], o2[1]); w.y = cvt2(o2[2], o2[3]); *(LAS u32x2*)(buf + SB_XB + sl * 144 + col * 2) = w;
;     w.x = cvt2(o3[0], o3[1]); w.y = cvt2(o3[2], o3[3]); *(LAS u32x2*)(buf + SB_XB + (16 + sl) * 144 + col * 2) = w;
; #pragma unroll
;     for (int i = 0; i < 4; ++i) {
;         *(LAS unsigned short*)(buf + SB_XBT + (col + i) * 80 + sl * 2) = (unsigned short)(cvt2(o2[i], 0.f) & 0xffffu);
;         *(LAS unsigned short*)(buf + SB_XBT + (col + i) * 80 + (16 + sl) * 2) = (unsigned short)(cvt2(o3[i], 0.f) & 0xffffu);
;         *(LAS unsigned short*)(buf + SB_VT + (col + i) * 48 + sl * 2) = (unsigned short)(cvt2(v[i], 0.f) & 0xffffu); }
;     if (sl == SC_CH - 1) *(LAS f32x4*)(buf + SB_WE + col * 4) = we;
.Lrw_ld_rare:
	s_cmpk_gt_u32 s69, 0xfc
	s_cbranch_scc1 .LBB0_613
	s_add_i32 s0, s70, -1
	s_and_b32 s0, s0, 3
	s_mulk_i32 s0, 0x4500
	v_add_u32_e32 v190, s0, v250
	s_waitcnt vmcnt(0)
	s_bitcmp1_b32 s69, 0
	s_cbranch_scc1 .Lrw_ld_o_tail
	v_lshlrev_b32_e32 v32, 16, v76
	v_and_b32_e32 v33, 0xffff0000, v76
	v_lshlrev_b32_e32 v34, 16, v77
	v_and_b32_e32 v35, 0xffff0000, v77
	v_mul_f32_e32 v52, 0x3fb8aa3b, v32
	v_mul_f32_e32 v53, 0x3fb8aa3b, v33
	v_mul_f32_e32 v54, 0x3fb8aa3b, v34
	v_mul_f32_e32 v55, 0x3fb8aa3b, v35
	v_add_f32_dpp v52, v52, v52 row_shr:4 row_mask:0xf bank_mask:0xf
	v_add_f32_dpp v53, v53, v53 row_shr:4 row_mask:0xf bank_mask:0xf
	v_add_f32_dpp v54, v54, v54 row_shr:4 row_mask:0xf bank_mask:0xf
	v_add_f32_dpp v55, v55, v55 row_shr:4 row_mask:0xf bank_mask:0xf
	v_add_f32_dpp v52, v52, v52 row_shr:8 row_mask:0xf bank_mask:0xf
	v_add_f32_dpp v53, v53, v53 row_shr:8 row_mask:0xf bank_mask:0xf
	v_add_f32_dpp v54, v54, v54 row_shr:8 row_mask:0xf bank_mask:0xf
	v_add_f32_dpp v55, v55, v55 row_shr:8 row_mask:0xf bank_mask:0xf
	ds_bpermute_b32 v60, v251, v52
	ds_bpermute_b32 v61, v251, v53
	ds_bpermute_b32 v62, v251, v54
	ds_bpermute_b32 v63, v251, v55
	ds_write_b16 v190, v82 offset:14336
	ds_write_b16_d16_hi v190, v82 offset:14384
	ds_write_b16 v190, v83 offset:14432
	ds_write_b16_d16_hi v190, v83 offset:14480
	v_lshlrev_b32_e32 v36, 16, v78
	v_and_b32_e32 v37, 0xffff0000, v78
	v_lshlrev_b32_e32 v38, 16, v79
	v_and_b32_e32 v39, 0xffff0000, v79
	v_lshlrev_b32_e32 v40, 16, v80
	v_and_b32_e32 v41, 0xffff0000, v80
	v_lshlrev_b32_e32 v42, 16, v81
	v_and_b32_e32 v43, 0xffff0000, v81
	v_lshlrev_b32_e32 v44, 16, v84
	v_and_b32_e32 v45, 0xffff0000, v84
	v_lshlrev_b32_e32 v46, 16, v85
	v_and_b32_e32 v47, 0xffff0000, v85
	v_lshlrev_b32_e32 v48, 16, v86
	v_and_b32_e32 v49, 0xffff0000, v86
	v_lshlrev_b32_e32 v50, 16, v87
	v_and_b32_e32 v51, 0xffff0000, v87
	s_waitcnt lgkmcnt(4)
	v_fmac_f32_e32 v52, v60, v253
	v_fmac_f32_e32 v53, v61, v253
	v_fmac_f32_e32 v54, v62, v253
	v_fmac_f32_e32 v55, v63, v253
	ds_bpermute_b32 v60, v252, v52
	ds_bpermute_b32 v61, v252, v53
	ds_bpermute_b32 v62, v252, v54
	ds_bpermute_b32 v63, v252, v55
	s_waitcnt lgkmcnt(0)
	v_fmac_f32_e32 v52, v60, v245
	v_fmac_f32_e32 v53, v61, v245
	v_fmac_f32_e32 v54, v62, v245
	v_fmac_f32_e32 v55, v63, v245
	s_branch .Lrw_ldfin
.Lrw_ld_o_tail:
	v_lshlrev_b32_e32 v32, 16, v222
	v_and_b32_e32 v33, 0xffff0000, v222
	v_lshlrev_b32_e32 v34, 16, v223
	v_and_b32_e32 v35, 0xffff0000, v223
	v_mul_f32_e32 v52, 0x3fb8aa3b, v32
	v_mul_f32_e32 v53, 0x3fb8aa3b, v33
	v_mul_f32_e32 v54, 0x3fb8aa3b, v34
	v_mul_f32_e32 v55, 0x3fb8aa3b, v35
	v_add_f32_dpp v52, v52, v52 row_shr:4 row_mask:0xf bank_mask:0xf
	v_add_f32_dpp v53, v53, v53 row_shr:4 row_mask:0xf bank_mask:0xf
	v_add_f32_dpp v54, v54, v54 row_shr:4 row_mask:0xf bank_mask:0xf
	v_add_f32_dpp v55, v55, v55 row_shr:4 row_mask:0xf bank_mask:0xf
	v_add_f32_dpp v52, v52, v52 row_shr:8 row_mask:0xf bank_mask:0xf
	v_add_f32_dpp v53, v53, v53 row_shr:8 row_mask:0xf bank_mask:0xf
	v_add_f32_dpp v54, v54, v54 row_shr:8 row_mask:0xf bank_mask:0xf
	v_add_f32_dpp v55, v55, v55 row_shr:8 row_mask:0xf bank_mask:0xf
	ds_bpermute_b32 v60, v251, v52
	ds_bpermute_b32 v61, v251, v53
	ds_bpermute_b32 v62, v251, v54
	ds_bpermute_b32 v63, v251, v55
	ds_write_b16 v190, v228 offset:14336
	ds_write_b16_d16_hi v190, v228 offset:14384
	ds_write_b16 v190, v229 offset:14432
	ds_write_b16_d16_hi v190, v229 offset:14480
	v_lshlrev_b32_e32 v36, 16, v224
	v_and_b32_e32 v37, 0xffff0000, v224
	v_lshlrev_b32_e32 v38, 16, v225
	v_and_b32_e32 v39, 0xffff0000, v225
	v_lshlrev_b32_e32 v40, 16, v226
	v_and_b32_e32 v41, 0xffff0000, v226
	v_lshlrev_b32_e32 v42, 16, v227
	v_and_b32_e32 v43, 0xffff0000, v227
	v_lshlrev_b32_e32 v44, 16, v230
	v_and_b32_e32 v45, 0xffff0000, v230
	v_lshlrev_b32_e32 v46, 16, v231
	v_and_b32_e32 v47, 0xffff0000, v231
	v_lshlrev_b32_e32 v48, 16, v232
	v_and_b32_e32 v49, 0xffff0000, v232
	v_lshlrev_b32_e32 v50, 16, v233
	v_and_b32_e32 v51, 0xffff0000, v233
	s_waitcnt lgkmcnt(4)
	v_fmac_f32_e32 v52, v60, v253
	v_fmac_f32_e32 v53, v61, v253
	v_fmac_f32_e32 v54, v62, v253
	v_fmac_f32_e32 v55, v63, v253
	ds_bpermute_b32 v60, v252, v52
	ds_bpermute_b32 v61, v252, v53
	ds_bpermute_b32 v62, v252, v54
	ds_bpermute_b32 v63, v252, v55
	s_waitcnt lgkmcnt(0)
	v_fmac_f32_e32 v52, v60, v245
	v_fmac_f32_e32 v53, v61, v245
	v_fmac_f32_e32 v54, v62, v245
	v_fmac_f32_e32 v55, v63, v245
.Lrw_ldfin:
	v_exp_f32_e32 v68, v52
	v_exp_f32_e32 v69, v53
	v_exp_f32_e32 v70, v54
	v_exp_f32_e32 v71, v55
	v_add_u32_e32 v221, s0, v249
	v_pk_mul_f32 v[200:201], v[68:69], v[48:49]
	v_pk_mul_f32 v[202:203], v[70:71], v[50:51]
	v_pk_mul_f32 v[204:205], v[68:69], v[36:37]
	v_pk_mul_f32 v[206:207], v[70:71], v[38:39]
	v_cvt_pk_bf16_f32 v214, v200, v201
	v_cvt_pk_bf16_f32 v215, v202, v203
	v_cvt_pk_bf16_f32 v216, v204, v205
	v_cvt_pk_bf16_f32 v217, v206, v207
	ds_write_b16 v221, v214 offset:9216
	ds_write_b16_d16_hi v221, v214 offset:9296
	ds_write_b16 v221, v215 offset:9376
	ds_write_b16_d16_hi v221, v215 offset:9456
	ds_write_b16 v221, v216 offset:9248
	ds_write_b16_d16_hi v221, v216 offset:9328
	ds_write_b16 v221, v217 offset:9408
	ds_write_b16_d16_hi v221, v217 offset:9488
	v_fmamk_f32 v56, v32, 0xbfb8aa3b, v52
	v_fmamk_f32 v57, v33, 0xbfb8aa3b, v53
	v_fmamk_f32 v58, v34, 0xbfb8aa3b, v54
	v_fmamk_f32 v59, v35, 0xbfb8aa3b, v55
	v_exp_f32_e64 v64, -v52
	v_exp_f32_e64 v65, -v53
	v_exp_f32_e64 v66, -v54
	v_exp_f32_e64 v67, -v55
	v_exp_f32_e64 v192, -v56
	v_exp_f32_e64 v193, -v57
	v_exp_f32_e64 v194, -v58
	v_exp_f32_e64 v195, -v59
	v_add_u32_e32 v191, s0, v248
	v_pk_mul_f32 v[208:209], v[64:65], v[40:41]
	v_pk_mul_f32 v[210:211], v[66:67], v[42:43]
	v_pk_mul_f32 v[196:197], v[192:193], v[44:45]
	v_pk_mul_f32 v[198:199], v[194:195], v[46:47]
	v_cvt_pk_bf16_f32 v218, v208, v209
	v_cvt_pk_bf16_f32 v219, v210, v211
	v_cvt_pk_bf16_f32 v212, v196, v197
	v_cvt_pk_bf16_f32 v213, v198, v199
	v_add_u32_e32 v220, 0x900, v191
	ds_write2st64_b64 v220, v[218:219], v[216:217] offset1:9
	ds_write2st64_b64 v191, v[212:213], v[214:215] offset1:9
	s_and_saveexec_b64 s[42:43], s[14:15]
	v_add_u32_e32 v60, s0, v188
	ds_write_b128 v60, v[64:67] offset:17408
	s_or_b64 exec, exec, s[42:43]
	s_branch .LBB0_613
